# speedup vs baseline: 1.1301x; 1.0041x over previous
.LBB0_262:
	v_readfirstlane_b32 s98, v135
	s_nop 0
	s_lshr_b32 s98, s98, 8
	v_mov_b32_e32 v0, 0
	s_mov_b32 s38, 1
	s_mov_b32 s39, 0
	v_mov_b32_e32 v128, v199
	v_mov_b32_e32 v129, v198
	v_mov_b32_e32 v130, v196
	v_mov_b32_e32 v131, v193
	v_mov_b32_e32 v144, v203
	v_mov_b32_e32 v145, v200
	v_mov_b32_e32 v146, v201
	v_mov_b32_e32 v147, v202
	v_mov_b32_e32 v148, v192
	v_mov_b32_e32 v149, v194
	v_mov_b32_e32 v150, v195
	v_mov_b32_e32 v151, v197
	v_mov_b32_e32 v1, v0
	v_mov_b32_e32 v2, v0
	v_mov_b32_e32 v3, v0
	v_mov_b32_e32 v4, v0
	v_mov_b32_e32 v5, v0
	v_mov_b32_e32 v6, v0
	v_mov_b32_e32 v7, v0
	v_mov_b32_e32 v8, v0
	v_mov_b32_e32 v9, v0
	v_mov_b32_e32 v10, v0
	v_mov_b32_e32 v11, v0
	v_mov_b32_e32 v12, v0
	v_mov_b32_e32 v13, v0
	v_mov_b32_e32 v14, v0
	v_mov_b32_e32 v15, v0
	v_mov_b32_e32 v16, v0
	v_mov_b32_e32 v17, v0
	v_mov_b32_e32 v18, v0
	v_mov_b32_e32 v19, v0
	v_mov_b32_e32 v20, v0
	v_mov_b32_e32 v21, v0
	v_mov_b32_e32 v22, v0
	v_mov_b32_e32 v23, v0
	v_mov_b32_e32 v24, v0
	v_mov_b32_e32 v25, v0
	v_mov_b32_e32 v26, v0
	v_mov_b32_e32 v27, v0
	v_mov_b32_e32 v28, v0
	v_mov_b32_e32 v29, v0
	v_mov_b32_e32 v30, v0
	v_mov_b32_e32 v31, v0
	v_mov_b32_e32 v32, v0
	v_mov_b32_e32 v33, v0
	v_mov_b32_e32 v34, v0
	v_mov_b32_e32 v35, v0
	v_mov_b32_e32 v36, v0
	v_mov_b32_e32 v37, v0
	v_mov_b32_e32 v38, v0
	v_mov_b32_e32 v39, v0
	v_mov_b32_e32 v40, v0
	v_mov_b32_e32 v41, v0
	v_mov_b32_e32 v42, v0
	v_mov_b32_e32 v43, v0
	v_mov_b32_e32 v44, v0
	v_mov_b32_e32 v45, v0
	v_mov_b32_e32 v46, v0
	v_mov_b32_e32 v47, v0
	v_mov_b32_e32 v48, v0
	v_mov_b32_e32 v49, v0
	v_mov_b32_e32 v50, v0
	v_mov_b32_e32 v51, v0
	v_mov_b32_e32 v52, v0
	v_mov_b32_e32 v53, v0
	v_mov_b32_e32 v54, v0
	v_mov_b32_e32 v55, v0
	v_mov_b32_e32 v56, v0
	v_mov_b32_e32 v57, v0
	v_mov_b32_e32 v58, v0
	v_mov_b32_e32 v59, v0
	v_mov_b32_e32 v60, v0
	v_mov_b32_e32 v61, v0
	v_mov_b32_e32 v62, v0
	v_mov_b32_e32 v63, v0
	v_mov_b32_e32 v64, v0
	v_mov_b32_e32 v65, v0
	v_mov_b32_e32 v66, v0
	v_mov_b32_e32 v67, v0
	v_mov_b32_e32 v68, v0
	v_mov_b32_e32 v69, v0
	v_mov_b32_e32 v70, v0
	v_mov_b32_e32 v71, v0
	v_mov_b32_e32 v72, v0
	v_mov_b32_e32 v73, v0
	v_mov_b32_e32 v74, v0
	v_mov_b32_e32 v75, v0
	v_mov_b32_e32 v76, v0
	v_mov_b32_e32 v77, v0
	v_mov_b32_e32 v78, v0
	v_mov_b32_e32 v79, v0
	v_mov_b32_e32 v80, v0
	v_mov_b32_e32 v81, v0
	v_mov_b32_e32 v82, v0
	v_mov_b32_e32 v83, v0
	v_mov_b32_e32 v84, v0
	v_mov_b32_e32 v85, v0
	v_mov_b32_e32 v86, v0
	v_mov_b32_e32 v87, v0
	v_mov_b32_e32 v88, v0
	v_mov_b32_e32 v89, v0
	v_mov_b32_e32 v90, v0
	v_mov_b32_e32 v91, v0
	v_mov_b32_e32 v92, v0
	v_mov_b32_e32 v93, v0
	v_mov_b32_e32 v94, v0
	v_mov_b32_e32 v95, v0
	v_mov_b32_e32 v96, v0
	v_mov_b32_e32 v97, v0
	v_mov_b32_e32 v98, v0
	v_mov_b32_e32 v99, v0
	v_mov_b32_e32 v100, v0
	v_mov_b32_e32 v101, v0
	v_mov_b32_e32 v102, v0
	v_mov_b32_e32 v103, v0
	v_mov_b32_e32 v104, v0
	v_mov_b32_e32 v105, v0
	v_mov_b32_e32 v106, v0
	v_mov_b32_e32 v107, v0
	v_mov_b32_e32 v108, v0
	v_mov_b32_e32 v109, v0
	v_mov_b32_e32 v110, v0
	v_mov_b32_e32 v111, v0
	v_mov_b32_e32 v112, v0
	v_mov_b32_e32 v113, v0
	v_mov_b32_e32 v114, v0
	v_mov_b32_e32 v115, v0
	v_mov_b32_e32 v116, v0
	v_mov_b32_e32 v117, v0
	v_mov_b32_e32 v118, v0
	v_mov_b32_e32 v119, v0
	v_mov_b32_e32 v120, v0
	v_mov_b32_e32 v121, v0
	v_mov_b32_e32 v122, v0
	v_mov_b32_e32 v123, v0
	v_mov_b32_e32 v124, v0
	v_mov_b32_e32 v125, v0
	v_mov_b32_e32 v126, v0
	v_mov_b32_e32 v127, v0
.LBB0_263:
	s_add_i32 s4, s49, s38
	s_add_i32 s4, s4, -1
	s_and_b32 s60, s4, 1
	s_waitcnt vmcnt(0) lgkmcnt(0)
	s_barrier
	s_cmp_eq_u32 s98, 0
	s_cbranch_scc0 .Lg1_top
	s_cmp_ge_u32 s38, s23
	s_cbranch_scc0 .Lg0_norm
	s_load_dword s4, s[72:73], 0x10
	s_load_dword s6, s[72:73], 0x0
	s_waitcnt lgkmcnt(0)
	s_lshr_b32 s4, s4, 16
	s_cmp_lg_u32 s4, 0
	s_cselect_b64 s[4:5], -1, 0
	s_cmp_lg_u64 s[4:5], 0
	s_addc_u32 s7, s6, s17
	s_cmp_lt_i32 s7, s85
	s_mov_b64 s[4:5], -1
	s_cbranch_scc1 .LBB0_266a
	s_lshl_b32 s6, s60, 16
	s_mov_b64 s[4:5], 0

.Lg0_comp:
	s_waitcnt lgkmcnt(2)
	v_mfma_f32_16x16x32_bf16 v[124:127], v[128:131], v[204:207], v[124:127]
	ds_read_b128 v[240:243], v232 offset:6144
	v_mfma_f32_16x16x32_bf16 v[120:123], v[144:147], v[204:207], v[120:123]
	v_mfma_f32_16x16x32_bf16 v[116:119], v[148:151], v[204:207], v[116:119]
	v_mfma_f32_16x16x32_bf16 v[112:115], v[154:157], v[204:207], v[112:115]
	s_waitcnt lgkmcnt(2)
	v_mfma_f32_16x16x32_bf16 v[108:111], v[128:131], v[208:211], v[108:111]
	ds_read_b128 v[204:207], v232 offset:8192
	v_mfma_f32_16x16x32_bf16 v[104:107], v[144:147], v[208:211], v[104:107]
	v_mfma_f32_16x16x32_bf16 v[100:103], v[148:151], v[208:211], v[100:103]
	v_mfma_f32_16x16x32_bf16 v[96:99], v[154:157], v[208:211], v[96:99]
	s_waitcnt lgkmcnt(2)
	v_mfma_f32_16x16x32_bf16 v[92:95], v[128:131], v[212:215], v[92:95]
	ds_read_b128 v[208:211], v232 offset:10240
	ds_read_b128 v[216:219], v153 offset:33792
	v_mfma_f32_16x16x32_bf16 v[88:91], v[144:147], v[212:215], v[88:91]
	v_mfma_f32_16x16x32_bf16 v[84:87], v[148:151], v[212:215], v[84:87]
	v_mfma_f32_16x16x32_bf16 v[80:83], v[154:157], v[212:215], v[80:83]
	s_waitcnt lgkmcnt(3)
	v_mfma_f32_16x16x32_bf16 v[76:79], v[128:131], v[240:243], v[76:79]
	ds_read_b128 v[212:215], v232 offset:12288
	ds_read_b128 v[220:223], v153 offset:35840
	v_mfma_f32_16x16x32_bf16 v[72:75], v[144:147], v[240:243], v[72:75]
	v_mfma_f32_16x16x32_bf16 v[68:71], v[148:151], v[240:243], v[68:71]
	v_mfma_f32_16x16x32_bf16 v[64:67], v[154:157], v[240:243], v[64:67]
	s_waitcnt lgkmcnt(4)
	v_mfma_f32_16x16x32_bf16 v[60:63], v[128:131], v[204:207], v[60:63]
	ds_read_b128 v[240:243], v232 offset:14336
	ds_read_b128 v[224:227], v153 offset:37888
	v_mfma_f32_16x16x32_bf16 v[56:59], v[144:147], v[204:207], v[56:59]
	v_mfma_f32_16x16x32_bf16 v[52:55], v[148:151], v[204:207], v[52:55]
	v_mfma_f32_16x16x32_bf16 v[48:51], v[154:157], v[204:207], v[48:51]
	s_waitcnt lgkmcnt(5)
	v_mfma_f32_16x16x32_bf16 v[44:47], v[128:131], v[208:211], v[44:47]
	ds_read_b128 v[204:207], v232 offset:1024
	ds_read_b128 v[228:231], v153 offset:39936
	v_mfma_f32_16x16x32_bf16 v[40:43], v[144:147], v[208:211], v[40:43]
	v_mfma_f32_16x16x32_bf16 v[36:39], v[148:151], v[208:211], v[36:39]
	v_mfma_f32_16x16x32_bf16 v[32:35], v[154:157], v[208:211], v[32:35]
	s_waitcnt lgkmcnt(5)
	v_mfma_f32_16x16x32_bf16 v[28:31], v[128:131], v[212:215], v[28:31]
	ds_read_b128 v[208:211], v232 offset:3072
	v_mfma_f32_16x16x32_bf16 v[24:27], v[144:147], v[212:215], v[24:27]
	v_mfma_f32_16x16x32_bf16 v[20:23], v[148:151], v[212:215], v[20:23]
	v_mfma_f32_16x16x32_bf16 v[16:19], v[154:157], v[212:215], v[16:19]
	s_waitcnt lgkmcnt(4)
	v_mfma_f32_16x16x32_bf16 v[12:15], v[128:131], v[240:243], v[12:15]
	ds_read_b128 v[212:215], v232 offset:5120
	v_mfma_f32_16x16x32_bf16 v[8:11], v[144:147], v[240:243], v[8:11]
	v_mfma_f32_16x16x32_bf16 v[4:7], v[148:151], v[240:243], v[4:7]
	v_mfma_f32_16x16x32_bf16 v[0:3], v[154:157], v[240:243], v[0:3]
	s_waitcnt lgkmcnt(2)
	v_mfma_f32_16x16x32_bf16 v[124:127], v[216:219], v[204:207], v[124:127]
	ds_read_b128 v[240:243], v232 offset:7168
	v_mfma_f32_16x16x32_bf16 v[120:123], v[220:223], v[204:207], v[120:123]
	v_mfma_f32_16x16x32_bf16 v[116:119], v[224:227], v[204:207], v[116:119]
	v_mfma_f32_16x16x32_bf16 v[112:115], v[228:231], v[204:207], v[112:115]
	s_waitcnt lgkmcnt(2)
	v_mfma_f32_16x16x32_bf16 v[108:111], v[216:219], v[208:211], v[108:111]
	ds_read_b128 v[204:207], v232 offset:9216
	v_mfma_f32_16x16x32_bf16 v[104:107], v[220:223], v[208:211], v[104:107]
	v_mfma_f32_16x16x32_bf16 v[100:103], v[224:227], v[208:211], v[100:103]
	v_mfma_f32_16x16x32_bf16 v[96:99], v[228:231], v[208:211], v[96:99]
	s_waitcnt lgkmcnt(2)
	v_mfma_f32_16x16x32_bf16 v[92:95], v[216:219], v[212:215], v[92:95]
	ds_read_b128 v[208:211], v232 offset:11264
	v_mfma_f32_16x16x32_bf16 v[88:91], v[220:223], v[212:215], v[88:91]
	v_mfma_f32_16x16x32_bf16 v[84:87], v[224:227], v[212:215], v[84:87]
	v_mfma_f32_16x16x32_bf16 v[80:83], v[228:231], v[212:215], v[80:83]
	s_waitcnt lgkmcnt(2)
	v_mfma_f32_16x16x32_bf16 v[76:79], v[216:219], v[240:243], v[76:79]
	ds_read_b128 v[212:215], v232 offset:13312
	v_mfma_f32_16x16x32_bf16 v[72:75], v[220:223], v[240:243], v[72:75]
	v_mfma_f32_16x16x32_bf16 v[68:71], v[224:227], v[240:243], v[68:71]
	v_mfma_f32_16x16x32_bf16 v[64:67], v[228:231], v[240:243], v[64:67]
	s_waitcnt lgkmcnt(2)
	v_mfma_f32_16x16x32_bf16 v[60:63], v[216:219], v[204:207], v[60:63]
	ds_read_b128 v[240:243], v232 offset:15360
	v_mfma_f32_16x16x32_bf16 v[56:59], v[220:223], v[204:207], v[56:59]
	v_mfma_f32_16x16x32_bf16 v[52:55], v[224:227], v[204:207], v[52:55]
	v_mfma_f32_16x16x32_bf16 v[48:51], v[228:231], v[204:207], v[48:51]
	s_waitcnt lgkmcnt(2)
	v_mfma_f32_16x16x32_bf16 v[44:47], v[216:219], v[208:211], v[44:47]
	v_mfma_f32_16x16x32_bf16 v[40:43], v[220:223], v[208:211], v[40:43]
	v_mfma_f32_16x16x32_bf16 v[36:39], v[224:227], v[208:211], v[36:39]
	v_mfma_f32_16x16x32_bf16 v[32:35], v[228:231], v[208:211], v[32:35]
	s_waitcnt lgkmcnt(1)
	v_mfma_f32_16x16x32_bf16 v[28:31], v[216:219], v[212:215], v[28:31]
	v_mfma_f32_16x16x32_bf16 v[24:27], v[220:223], v[212:215], v[24:27]
	v_mfma_f32_16x16x32_bf16 v[20:23], v[224:227], v[212:215], v[20:23]
	v_mfma_f32_16x16x32_bf16 v[16:19], v[228:231], v[212:215], v[16:19]
	s_waitcnt lgkmcnt(0)
	v_mfma_f32_16x16x32_bf16 v[12:15], v[216:219], v[240:243], v[12:15]
	v_mfma_f32_16x16x32_bf16 v[8:11], v[220:223], v[240:243], v[8:11]
	v_mfma_f32_16x16x32_bf16 v[4:7], v[224:227], v[240:243], v[4:7]
	v_mfma_f32_16x16x32_bf16 v[0:3], v[228:231], v[240:243], v[0:3]
	s_add_i32 s38, s38, 1
	s_addk_i32 s39, 0x80
	s_cmp_eq_u32 s65, s39
	s_cbranch_scc0 .LBB0_263
	s_branch .LBB0_289
.Lg1_top:
	s_cmp_ge_u32 s38, s23
	s_cbranch_scc0 .Lg1_norm
	s_cmp_eq_u32 s38, 1
	s_cbranch_scc1 .Lg1_last_notail
	v_mfma_f32_16x16x32_bf16 v[60:63], v[216:219], v[204:207], v[60:63]
	v_mfma_f32_16x16x32_bf16 v[56:59], v[220:223], v[204:207], v[56:59]
	v_mfma_f32_16x16x32_bf16 v[52:55], v[224:227], v[204:207], v[52:55]
	v_mfma_f32_16x16x32_bf16 v[48:51], v[228:231], v[204:207], v[48:51]
	v_mfma_f32_16x16x32_bf16 v[44:47], v[216:219], v[208:211], v[44:47]
	v_mfma_f32_16x16x32_bf16 v[40:43], v[220:223], v[208:211], v[40:43]
	v_mfma_f32_16x16x32_bf16 v[36:39], v[224:227], v[208:211], v[36:39]
	v_mfma_f32_16x16x32_bf16 v[32:35], v[228:231], v[208:211], v[32:35]
	v_mfma_f32_16x16x32_bf16 v[28:31], v[216:219], v[212:215], v[28:31]
	v_mfma_f32_16x16x32_bf16 v[24:27], v[220:223], v[212:215], v[24:27]
	v_mfma_f32_16x16x32_bf16 v[20:23], v[224:227], v[212:215], v[20:23]
	v_mfma_f32_16x16x32_bf16 v[16:19], v[228:231], v[212:215], v[16:19]
	v_mfma_f32_16x16x32_bf16 v[12:15], v[216:219], v[240:243], v[12:15]
	v_mfma_f32_16x16x32_bf16 v[8:11], v[220:223], v[240:243], v[8:11]
	v_mfma_f32_16x16x32_bf16 v[4:7], v[224:227], v[240:243], v[4:7]
	v_mfma_f32_16x16x32_bf16 v[0:3], v[228:231], v[240:243], v[0:3]
.Lg1_last_notail:
	s_load_dword s4, s[72:73], 0x10
	s_load_dword s6, s[72:73], 0x0
	s_waitcnt lgkmcnt(0)
	s_lshr_b32 s4, s4, 16
	s_cmp_lg_u32 s4, 0
	s_cselect_b64 s[4:5], -1, 0
	s_cmp_lg_u64 s[4:5], 0
	s_addc_u32 s7, s6, s17
	s_cmp_lt_i32 s7, s85
	s_mov_b64 s[4:5], -1
	s_cbranch_scc1 .LBB0_266b
	s_lshl_b32 s6, s60, 16
	s_mov_b64 s[4:5], 0

.Lg1_norm:
	s_cmp_eq_u32 s38, 1
	s_cbranch_scc1 .Lg1_first
	s_lshl_b32 s6, s60, 16
	v_mov_b32_e32 v152, s6
	v_add3_u32 v153, v152, v171, v170
	v_add3_u32 v232, v152, v171, v173
	v_mfma_f32_16x16x32_bf16 v[60:63], v[216:219], v[204:207], v[60:63]
	ds_read_b128 v[128:131], v153 offset:32768
	ds_read_b128 v[144:147], v153 offset:34816
	v_mfma_f32_16x16x32_bf16 v[56:59], v[220:223], v[204:207], v[56:59]
	v_mfma_f32_16x16x32_bf16 v[52:55], v[224:227], v[204:207], v[52:55]
	v_mfma_f32_16x16x32_bf16 v[48:51], v[228:231], v[204:207], v[48:51]
	v_mfma_f32_16x16x32_bf16 v[44:47], v[216:219], v[208:211], v[44:47]
	ds_read_b128 v[204:207], v232 offset:0
	ds_read_b128 v[148:151], v153 offset:36864
	v_mfma_f32_16x16x32_bf16 v[40:43], v[220:223], v[208:211], v[40:43]
	v_mfma_f32_16x16x32_bf16 v[36:39], v[224:227], v[208:211], v[36:39]
	v_mfma_f32_16x16x32_bf16 v[32:35], v[228:231], v[208:211], v[32:35]
	v_mfma_f32_16x16x32_bf16 v[28:31], v[216:219], v[212:215], v[28:31]
	ds_read_b128 v[208:211], v232 offset:2048
	ds_read_b128 v[154:157], v153 offset:38912
	v_mfma_f32_16x16x32_bf16 v[24:27], v[220:223], v[212:215], v[24:27]
	v_mfma_f32_16x16x32_bf16 v[20:23], v[224:227], v[212:215], v[20:23]
	v_mfma_f32_16x16x32_bf16 v[16:19], v[228:231], v[212:215], v[16:19]
	v_mfma_f32_16x16x32_bf16 v[12:15], v[216:219], v[240:243], v[12:15]
	ds_read_b128 v[212:215], v232 offset:4096
	v_mfma_f32_16x16x32_bf16 v[8:11], v[220:223], v[240:243], v[8:11]
	v_mfma_f32_16x16x32_bf16 v[4:7], v[224:227], v[240:243], v[4:7]
	v_mfma_f32_16x16x32_bf16 v[0:3], v[228:231], v[240:243], v[0:3]
	s_branch .Lg1_slim

.Lg1_slim:
	s_xor_b32 s4, s6, 0x10000
	v_readfirstlane_b32 s5, v137
	s_cmp_lt_u32 s38, s16
	s_cselect_b64 vcc, -1, 0
	s_add_i32 s4, s4, s5
	s_add_i32 s5, s39, s64
	s_add_i32 s7, s39, 0x80
	v_add_u32_e32 v239, s7, v192
	v_add_u32_e32 v244, s5, v193
	s_add_i32 m0, s4, 0x0
	v_cndmask_b32_e32 v239, v244, v239, vcc
	v_add_u32_e32 v245, s7, v202
	global_load_lds_dwordx4 v239, s[30:31]
	s_add_i32 m0, s4, 0x8000
	s_nop 0
	global_load_lds_dwordx4 v245, s[30:31]
	v_add_u32_e32 v239, s7, v194
	v_add_u32_e32 v244, s5, v196
	s_add_i32 m0, s4, 0x2000
	v_cndmask_b32_e32 v239, v244, v239, vcc
	v_add_u32_e32 v245, s7, v201
	global_load_lds_dwordx4 v239, s[30:31]
	s_add_i32 m0, s4, 0xa000
	s_nop 0
	global_load_lds_dwordx4 v245, s[30:31]
	v_add_u32_e32 v239, s7, v195
	v_add_u32_e32 v244, s5, v198
	s_add_i32 m0, s4, 0x4000
	v_cndmask_b32_e32 v239, v244, v239, vcc
	v_add_u32_e32 v245, s7, v200
	global_load_lds_dwordx4 v239, s[30:31]
	s_add_i32 m0, s4, 0xc000
	s_nop 0
	global_load_lds_dwordx4 v245, s[30:31]
	v_add_u32_e32 v239, s7, v197
	v_add_u32_e32 v244, s5, v199
	s_add_i32 m0, s4, 0x6000
	v_cndmask_b32_e32 v239, v244, v239, vcc
	v_add_u32_e32 v245, s7, v203
	global_load_lds_dwordx4 v239, s[30:31]
	s_add_i32 m0, s4, 0xe000
	s_nop 0
	global_load_lds_dwordx4 v245, s[30:31]
.Lg1_comp:
	s_waitcnt lgkmcnt(1)
	v_mfma_f32_16x16x32_bf16 v[124:127], v[128:131], v[204:207], v[124:127]
	ds_read_b128 v[240:243], v232 offset:6144
	v_mfma_f32_16x16x32_bf16 v[120:123], v[144:147], v[204:207], v[120:123]
	v_mfma_f32_16x16x32_bf16 v[116:119], v[148:151], v[204:207], v[116:119]
	v_mfma_f32_16x16x32_bf16 v[112:115], v[154:157], v[204:207], v[112:115]
	s_waitcnt lgkmcnt(2)
	v_mfma_f32_16x16x32_bf16 v[108:111], v[128:131], v[208:211], v[108:111]
	ds_read_b128 v[204:207], v232 offset:8192
	v_mfma_f32_16x16x32_bf16 v[104:107], v[144:147], v[208:211], v[104:107]
	v_mfma_f32_16x16x32_bf16 v[100:103], v[148:151], v[208:211], v[100:103]
	v_mfma_f32_16x16x32_bf16 v[96:99], v[154:157], v[208:211], v[96:99]
	s_waitcnt lgkmcnt(2)
	v_mfma_f32_16x16x32_bf16 v[92:95], v[128:131], v[212:215], v[92:95]
	ds_read_b128 v[208:211], v232 offset:10240
	ds_read_b128 v[216:219], v153 offset:33792
	v_mfma_f32_16x16x32_bf16 v[88:91], v[144:147], v[212:215], v[88:91]
	v_mfma_f32_16x16x32_bf16 v[84:87], v[148:151], v[212:215], v[84:87]
	v_mfma_f32_16x16x32_bf16 v[80:83], v[154:157], v[212:215], v[80:83]
	s_waitcnt lgkmcnt(3)
	v_mfma_f32_16x16x32_bf16 v[76:79], v[128:131], v[240:243], v[76:79]
	ds_read_b128 v[212:215], v232 offset:12288
	ds_read_b128 v[220:223], v153 offset:35840
	v_mfma_f32_16x16x32_bf16 v[72:75], v[144:147], v[240:243], v[72:75]
	v_mfma_f32_16x16x32_bf16 v[68:71], v[148:151], v[240:243], v[68:71]
	v_mfma_f32_16x16x32_bf16 v[64:67], v[154:157], v[240:243], v[64:67]
	s_waitcnt lgkmcnt(4)
	v_mfma_f32_16x16x32_bf16 v[60:63], v[128:131], v[204:207], v[60:63]
	ds_read_b128 v[240:243], v232 offset:14336
	ds_read_b128 v[224:227], v153 offset:37888
	v_mfma_f32_16x16x32_bf16 v[56:59], v[144:147], v[204:207], v[56:59]
	v_mfma_f32_16x16x32_bf16 v[52:55], v[148:151], v[204:207], v[52:55]
	v_mfma_f32_16x16x32_bf16 v[48:51], v[154:157], v[204:207], v[48:51]
	s_waitcnt lgkmcnt(5)
	v_mfma_f32_16x16x32_bf16 v[44:47], v[128:131], v[208:211], v[44:47]
	ds_read_b128 v[204:207], v232 offset:1024
	ds_read_b128 v[228:231], v153 offset:39936
	v_mfma_f32_16x16x32_bf16 v[40:43], v[144:147], v[208:211], v[40:43]
	v_mfma_f32_16x16x32_bf16 v[36:39], v[148:151], v[208:211], v[36:39]
	v_mfma_f32_16x16x32_bf16 v[32:35], v[154:157], v[208:211], v[32:35]
	s_waitcnt lgkmcnt(5)
	v_mfma_f32_16x16x32_bf16 v[28:31], v[128:131], v[212:215], v[28:31]
	ds_read_b128 v[208:211], v232 offset:3072
	v_mfma_f32_16x16x32_bf16 v[24:27], v[144:147], v[212:215], v[24:27]
	v_mfma_f32_16x16x32_bf16 v[20:23], v[148:151], v[212:215], v[20:23]
	v_mfma_f32_16x16x32_bf16 v[16:19], v[154:157], v[212:215], v[16:19]
	s_waitcnt lgkmcnt(4)
	v_mfma_f32_16x16x32_bf16 v[12:15], v[128:131], v[240:243], v[12:15]
	ds_read_b128 v[212:215], v232 offset:5120
	v_mfma_f32_16x16x32_bf16 v[8:11], v[144:147], v[240:243], v[8:11]
	v_mfma_f32_16x16x32_bf16 v[4:7], v[148:151], v[240:243], v[4:7]
	v_mfma_f32_16x16x32_bf16 v[0:3], v[154:157], v[240:243], v[0:3]
	s_waitcnt lgkmcnt(2)
	v_mfma_f32_16x16x32_bf16 v[124:127], v[216:219], v[204:207], v[124:127]
	ds_read_b128 v[240:243], v232 offset:7168
	v_mfma_f32_16x16x32_bf16 v[120:123], v[220:223], v[204:207], v[120:123]
	v_mfma_f32_16x16x32_bf16 v[116:119], v[224:227], v[204:207], v[116:119]
	v_mfma_f32_16x16x32_bf16 v[112:115], v[228:231], v[204:207], v[112:115]
	s_waitcnt lgkmcnt(2)
	v_mfma_f32_16x16x32_bf16 v[108:111], v[216:219], v[208:211], v[108:111]
	ds_read_b128 v[204:207], v232 offset:9216
	v_mfma_f32_16x16x32_bf16 v[104:107], v[220:223], v[208:211], v[104:107]
	v_mfma_f32_16x16x32_bf16 v[100:103], v[224:227], v[208:211], v[100:103]
	v_mfma_f32_16x16x32_bf16 v[96:99], v[228:231], v[208:211], v[96:99]
	s_waitcnt lgkmcnt(2)
	v_mfma_f32_16x16x32_bf16 v[92:95], v[216:219], v[212:215], v[92:95]
	ds_read_b128 v[208:211], v232 offset:11264
	v_mfma_f32_16x16x32_bf16 v[88:91], v[220:223], v[212:215], v[88:91]
	v_mfma_f32_16x16x32_bf16 v[84:87], v[224:227], v[212:215], v[84:87]
	v_mfma_f32_16x16x32_bf16 v[80:83], v[228:231], v[212:215], v[80:83]
	s_waitcnt lgkmcnt(2)
	v_mfma_f32_16x16x32_bf16 v[76:79], v[216:219], v[240:243], v[76:79]
	ds_read_b128 v[212:215], v232 offset:13312
	v_mfma_f32_16x16x32_bf16 v[72:75], v[220:223], v[240:243], v[72:75]
	v_mfma_f32_16x16x32_bf16 v[68:71], v[224:227], v[240:243], v[68:71]
	v_mfma_f32_16x16x32_bf16 v[64:67], v[228:231], v[240:243], v[64:67]
	ds_read_b128 v[240:243], v232 offset:15360
	s_add_i32 s38, s38, 1
	s_addk_i32 s39, 0x80
	s_cmp_eq_u32 s65, s39
	s_cbranch_scc0 .LBB0_263
	s_waitcnt lgkmcnt(0)
	v_mfma_f32_16x16x32_bf16 v[60:63], v[216:219], v[204:207], v[60:63]
	v_mfma_f32_16x16x32_bf16 v[56:59], v[220:223], v[204:207], v[56:59]
	v_mfma_f32_16x16x32_bf16 v[52:55], v[224:227], v[204:207], v[52:55]
	v_mfma_f32_16x16x32_bf16 v[48:51], v[228:231], v[204:207], v[48:51]
	v_mfma_f32_16x16x32_bf16 v[44:47], v[216:219], v[208:211], v[44:47]
	v_mfma_f32_16x16x32_bf16 v[40:43], v[220:223], v[208:211], v[40:43]
	v_mfma_f32_16x16x32_bf16 v[36:39], v[224:227], v[208:211], v[36:39]
	v_mfma_f32_16x16x32_bf16 v[32:35], v[228:231], v[208:211], v[32:35]
	v_mfma_f32_16x16x32_bf16 v[28:31], v[216:219], v[212:215], v[28:31]
	v_mfma_f32_16x16x32_bf16 v[24:27], v[220:223], v[212:215], v[24:27]
	v_mfma_f32_16x16x32_bf16 v[20:23], v[224:227], v[212:215], v[20:23]
	v_mfma_f32_16x16x32_bf16 v[16:19], v[228:231], v[212:215], v[16:19]
	v_mfma_f32_16x16x32_bf16 v[12:15], v[216:219], v[240:243], v[12:15]
	v_mfma_f32_16x16x32_bf16 v[8:11], v[220:223], v[240:243], v[8:11]
	v_mfma_f32_16x16x32_bf16 v[4:7], v[224:227], v[240:243], v[4:7]
	v_mfma_f32_16x16x32_bf16 v[0:3], v[228:231], v[240:243], v[0:3]

	.amdhsa_kernel _Z10fwd_kernel6Params
		.amdhsa_group_segment_fixed_size 156672
		.amdhsa_private_segment_fixed_size 0
		.amdhsa_kernarg_size 3504
		.amdhsa_user_sgpr_count 2
		.amdhsa_user_sgpr_dispatch_ptr 0
		.amdhsa_user_sgpr_queue_ptr 0
		.amdhsa_user_sgpr_kernarg_segment_ptr 1
		.amdhsa_user_sgpr_dispatch_id 0
		.amdhsa_user_sgpr_kernarg_preload_length 0
		.amdhsa_user_sgpr_kernarg_preload_offset 0
		.amdhsa_user_sgpr_private_segment_size 0
		.amdhsa_uses_dynamic_stack 0
		.amdhsa_enable_private_segment 0
		.amdhsa_system_sgpr_workgroup_id_x 1
		.amdhsa_system_sgpr_workgroup_id_y 0
		.amdhsa_system_sgpr_workgroup_id_z 0
		.amdhsa_system_sgpr_workgroup_info 0
		.amdhsa_system_vgpr_workitem_id 2
		.amdhsa_next_free_vgpr 248
		.amdhsa_next_free_sgpr 99
		.amdhsa_accum_offset 248
		.amdhsa_reserve_vcc 1
		.amdhsa_float_round_mode_32 0
		.amdhsa_float_round_mode_16_64 0
		.amdhsa_float_denorm_mode_32 3
		.amdhsa_float_denorm_mode_16_64 3
		.amdhsa_dx10_clamp 1
		.amdhsa_ieee_mode 1
		.amdhsa_fp16_overflow 0
		.amdhsa_tg_split 0
		.amdhsa_exception_fp_ieee_invalid_op 0
		.amdhsa_exception_fp_denorm_src 0
		.amdhsa_exception_fp_ieee_div_zero 0
		.amdhsa_exception_fp_ieee_overflow 0
		.amdhsa_exception_fp_ieee_underflow 0
		.amdhsa_exception_fp_ieee_inexact 0
		.amdhsa_exception_int_div_zero 0
	.end_amdhsa_kernel
